# GEMM K-loop: 8 s_nop M0 pads removed by reordering the address add behind the m0 write, 6 duplicate lgkmcnt(0) removed
# speedup vs baseline: 1.0589x; 1.0072x over previous
.LBB0_141:
	s_add_i32 s72, s40, 2
	s_add_u32 s68, s0, 0x80
	s_addc_u32 s41, s1, 0
	s_add_i32 s73, 0, 0x10000
	v_add_u32_e32 v140, s73, v183
	ds_read_b128 v[128:131], v140
	ds_read_b128 v[132:135], v140 offset:1024
	ds_read_b128 v[136:139], v140 offset:2048
	ds_read_b128 v[140:143], v140 offset:3072
	s_cmp_eq_u32 s10, s40
	s_cselect_b32 s40, s64, s68
	s_cselect_b32 s41, s65, s41
	s_cselect_b32 s69, s67, s71
	s_cselect_b32 s68, s66, s70
	v_lshl_add_u64 v[176:177], s[0:1], 0, v[192:193]
	s_add_i32 m0, s76, 0xc000
	ds_read_b128 v[144:147], v239
	ds_read_b128 v[148:151], v239 offset:1024
	ds_read_b128 v[152:155], v239 offset:2048
	ds_read_b128 v[156:159], v239 offset:3072
	ds_read_b128 v[160:163], v239 offset:4096
	ds_read_b128 v[164:167], v239 offset:5120
	ds_read_b128 v[168:171], v239 offset:6144
	ds_read_b128 v[172:175], v239 offset:7168
	global_load_lds_dwordx4 v[176:177], off
	s_add_i32 m0, s76, 0xe000
	v_lshl_add_u64 v[176:177], s[0:1], 0, v[194:195]
	global_load_lds_dwordx4 v[176:177], off
	s_waitcnt lgkmcnt(8)
	s_barrier
	s_waitcnt lgkmcnt(0)
	s_setprio 1
	v_mfma_f32_16x16x32_bf16 v[124:127], v[128:131], v[144:147], v[124:127]
	v_mfma_f32_16x16x32_bf16 v[116:119], v[136:139], v[144:147], v[116:119]
	v_mfma_f32_16x16x32_bf16 v[108:111], v[128:131], v[152:155], v[108:111]
	v_mfma_f32_16x16x32_bf16 v[100:103], v[136:139], v[152:155], v[100:103]
	v_mfma_f32_16x16x32_bf16 v[92:95], v[128:131], v[160:163], v[92:95]
	v_mfma_f32_16x16x32_bf16 v[84:87], v[136:139], v[160:163], v[84:87]
	v_mfma_f32_16x16x32_bf16 v[76:79], v[128:131], v[168:171], v[76:79]
	v_mfma_f32_16x16x32_bf16 v[68:71], v[136:139], v[168:171], v[68:71]
	v_mfma_f32_16x16x32_bf16 v[124:127], v[132:135], v[148:151], v[124:127]
	v_mfma_f32_16x16x32_bf16 v[116:119], v[140:143], v[148:151], v[116:119]
	v_mfma_f32_16x16x32_bf16 v[108:111], v[132:135], v[156:159], v[108:111]
	v_mfma_f32_16x16x32_bf16 v[100:103], v[140:143], v[156:159], v[100:103]
	v_mfma_f32_16x16x32_bf16 v[92:95], v[132:135], v[164:167], v[92:95]
	v_mfma_f32_16x16x32_bf16 v[84:87], v[140:143], v[164:167], v[84:87]
	v_mfma_f32_16x16x32_bf16 v[76:79], v[132:135], v[172:175], v[76:79]
	v_mfma_f32_16x16x32_bf16 v[68:71], v[140:143], v[172:175], v[68:71]
	s_setprio 0
	s_barrier
	s_add_i32 s80, 0, 0x14000
	s_add_i32 s73, s73, s33
	v_add_u32_e32 v204, s80, v183
	v_lshl_add_u64 v[208:209], s[68:69], 0, v[186:187]
	s_mov_b32 m0, s73
	ds_read_b128 v[176:179], v204
	ds_read_b128 v[196:199], v204 offset:1024
	ds_read_b128 v[200:203], v204 offset:2048
	ds_read_b128 v[204:207], v204 offset:3072
	global_load_lds_dwordx4 v[208:209], off
	s_add_i32 m0, s73, 0x2000
	v_lshl_add_u64 v[210:211], s[68:69], 0, v[190:191]
	global_load_lds_dwordx4 v[210:211], off
	s_barrier
	s_waitcnt lgkmcnt(0)
	s_setprio 1
	v_mfma_f32_16x16x32_bf16 v[120:123], v[176:179], v[144:147], v[120:123]
	v_mfma_f32_16x16x32_bf16 v[112:115], v[200:203], v[144:147], v[112:115]
	v_mfma_f32_16x16x32_bf16 v[104:107], v[176:179], v[152:155], v[104:107]
	v_mfma_f32_16x16x32_bf16 v[96:99], v[200:203], v[152:155], v[96:99]
	v_mfma_f32_16x16x32_bf16 v[88:91], v[176:179], v[160:163], v[88:91]
	v_mfma_f32_16x16x32_bf16 v[80:83], v[200:203], v[160:163], v[80:83]
	v_mfma_f32_16x16x32_bf16 v[72:75], v[176:179], v[168:171], v[72:75]
	v_mfma_f32_16x16x32_bf16 v[64:67], v[200:203], v[168:171], v[64:67]
	v_mfma_f32_16x16x32_bf16 v[120:123], v[196:199], v[148:151], v[120:123]
	v_mfma_f32_16x16x32_bf16 v[112:115], v[204:207], v[148:151], v[112:115]
	v_mfma_f32_16x16x32_bf16 v[104:107], v[196:199], v[156:159], v[104:107]
	v_mfma_f32_16x16x32_bf16 v[96:99], v[204:207], v[156:159], v[96:99]
	v_mfma_f32_16x16x32_bf16 v[88:91], v[196:199], v[164:167], v[88:91]
	v_mfma_f32_16x16x32_bf16 v[80:83], v[204:207], v[164:167], v[80:83]
	v_mfma_f32_16x16x32_bf16 v[72:75], v[196:199], v[172:175], v[72:75]
	v_mfma_f32_16x16x32_bf16 v[64:67], v[204:207], v[172:175], v[64:67]
	s_setprio 0
	s_mov_b32 m0, s76
	v_lshl_add_u64 v[212:213], s[40:41], 0, v[184:185]
	s_barrier
	ds_read_b128 v[144:147], v239 offset:16384
	ds_read_b128 v[148:151], v239 offset:17408
	ds_read_b128 v[152:155], v239 offset:18432
	ds_read_b128 v[156:159], v239 offset:19456
	ds_read_b128 v[160:163], v239 offset:20480
	ds_read_b128 v[164:167], v239 offset:21504
	ds_read_b128 v[168:171], v239 offset:22528
	ds_read_b128 v[172:175], v239 offset:23552
	global_load_lds_dwordx4 v[212:213], off
	s_mov_b32 m0, s4
	v_lshl_add_u64 v[214:215], s[40:41], 0, v[188:189]
	global_load_lds_dwordx4 v[214:215], off
	s_barrier
	s_waitcnt lgkmcnt(0)
	s_setprio 1
	v_mfma_f32_16x16x32_bf16 v[60:63], v[128:131], v[144:147], v[60:63]
	v_mfma_f32_16x16x32_bf16 v[52:55], v[136:139], v[144:147], v[52:55]
	v_mfma_f32_16x16x32_bf16 v[44:47], v[128:131], v[152:155], v[44:47]
	v_mfma_f32_16x16x32_bf16 v[36:39], v[136:139], v[152:155], v[36:39]
	v_mfma_f32_16x16x32_bf16 v[28:31], v[128:131], v[160:163], v[28:31]
	v_mfma_f32_16x16x32_bf16 v[20:23], v[136:139], v[160:163], v[20:23]
	v_mfma_f32_16x16x32_bf16 v[12:15], v[128:131], v[168:171], v[12:15]
	v_mfma_f32_16x16x32_bf16 v[4:7], v[136:139], v[168:171], v[4:7]
	v_mfma_f32_16x16x32_bf16 v[60:63], v[132:135], v[148:151], v[60:63]
	v_mfma_f32_16x16x32_bf16 v[52:55], v[140:143], v[148:151], v[52:55]
	v_mfma_f32_16x16x32_bf16 v[44:47], v[132:135], v[156:159], v[44:47]
	v_mfma_f32_16x16x32_bf16 v[36:39], v[140:143], v[156:159], v[36:39]
	v_mfma_f32_16x16x32_bf16 v[28:31], v[132:135], v[164:167], v[28:31]
	v_mfma_f32_16x16x32_bf16 v[20:23], v[140:143], v[164:167], v[20:23]
	v_mfma_f32_16x16x32_bf16 v[12:15], v[132:135], v[172:175], v[12:15]
	v_mfma_f32_16x16x32_bf16 v[4:7], v[140:143], v[172:175], v[4:7]
	s_setprio 0
	s_barrier
	s_add_u32 s68, s68, s98
	s_addc_u32 s69, s69, 0
	s_add_i32 s73, s80, s33
	v_lshl_add_u64 v[216:217], s[68:69], 0, v[186:187]
	s_mov_b32 m0, s73
	v_lshl_add_u64 v[218:219], s[68:69], 0, v[190:191]
	global_load_lds_dwordx4 v[216:217], off
	s_add_i32 m0, s73, 0x2000
	s_nop 0
	global_load_lds_dwordx4 v[218:219], off
	s_waitcnt vmcnt(6)
	s_barrier
	s_setprio 1
	v_mfma_f32_16x16x32_bf16 v[56:59], v[176:179], v[144:147], v[56:59]
	v_mfma_f32_16x16x32_bf16 v[48:51], v[200:203], v[144:147], v[48:51]
	v_mfma_f32_16x16x32_bf16 v[40:43], v[176:179], v[152:155], v[40:43]
	v_mfma_f32_16x16x32_bf16 v[32:35], v[200:203], v[152:155], v[32:35]
	v_mfma_f32_16x16x32_bf16 v[24:27], v[176:179], v[160:163], v[24:27]
	v_mfma_f32_16x16x32_bf16 v[16:19], v[200:203], v[160:163], v[16:19]
	v_mfma_f32_16x16x32_bf16 v[8:11], v[176:179], v[168:171], v[8:11]
	v_mfma_f32_16x16x32_bf16 v[0:3], v[200:203], v[168:171], v[0:3]
	v_mfma_f32_16x16x32_bf16 v[56:59], v[196:199], v[148:151], v[56:59]
	v_mfma_f32_16x16x32_bf16 v[48:51], v[204:207], v[148:151], v[48:51]
	v_mfma_f32_16x16x32_bf16 v[40:43], v[196:199], v[156:159], v[40:43]
	v_mfma_f32_16x16x32_bf16 v[32:35], v[204:207], v[156:159], v[32:35]
	v_mfma_f32_16x16x32_bf16 v[24:27], v[196:199], v[164:167], v[24:27]
	v_mfma_f32_16x16x32_bf16 v[16:19], v[204:207], v[164:167], v[16:19]
	v_mfma_f32_16x16x32_bf16 v[8:11], v[196:199], v[172:175], v[8:11]
	v_mfma_f32_16x16x32_bf16 v[0:3], v[204:207], v[172:175], v[0:3]
	s_setprio 0
	s_add_i32 s68, 0, 0x18000
	v_add_u32_e32 v140, s68, v183
	s_barrier
	ds_read_b128 v[128:131], v140
	ds_read_b128 v[132:135], v140 offset:1024
	ds_read_b128 v[136:139], v140 offset:2048
	ds_read_b128 v[140:143], v140 offset:3072
	s_add_u32 s40, s40, s98
	s_addc_u32 s41, s41, 0
	s_mov_b32 m0, s5
	v_lshl_add_u64 v[176:177], s[40:41], 0, v[184:185]
	ds_read_b128 v[144:147], v239 offset:32768
	ds_read_b128 v[148:151], v239 offset:33792
	ds_read_b128 v[152:155], v239 offset:34816
	ds_read_b128 v[156:159], v239 offset:35840
	ds_read_b128 v[160:163], v239 offset:36864
	ds_read_b128 v[164:167], v239 offset:37888
	ds_read_b128 v[168:171], v239 offset:38912
	ds_read_b128 v[172:175], v239 offset:39936
	global_load_lds_dwordx4 v[176:177], off
	s_mov_b32 m0, s6
	v_lshl_add_u64 v[176:177], s[40:41], 0, v[188:189]
	global_load_lds_dwordx4 v[176:177], off
	s_waitcnt lgkmcnt(8)
	s_barrier
	s_waitcnt lgkmcnt(0)
	s_setprio 1
	v_mfma_f32_16x16x32_bf16 v[124:127], v[128:131], v[144:147], v[124:127]
	v_mfma_f32_16x16x32_bf16 v[116:119], v[136:139], v[144:147], v[116:119]
	v_mfma_f32_16x16x32_bf16 v[108:111], v[128:131], v[152:155], v[108:111]
	v_mfma_f32_16x16x32_bf16 v[100:103], v[136:139], v[152:155], v[100:103]
	v_mfma_f32_16x16x32_bf16 v[92:95], v[128:131], v[160:163], v[92:95]
	v_mfma_f32_16x16x32_bf16 v[84:87], v[136:139], v[160:163], v[84:87]
	v_mfma_f32_16x16x32_bf16 v[76:79], v[128:131], v[168:171], v[76:79]
	v_mfma_f32_16x16x32_bf16 v[68:71], v[136:139], v[168:171], v[68:71]
	v_mfma_f32_16x16x32_bf16 v[124:127], v[132:135], v[148:151], v[124:127]
	v_mfma_f32_16x16x32_bf16 v[116:119], v[140:143], v[148:151], v[116:119]
	v_mfma_f32_16x16x32_bf16 v[108:111], v[132:135], v[156:159], v[108:111]
	v_mfma_f32_16x16x32_bf16 v[100:103], v[140:143], v[156:159], v[100:103]
	v_mfma_f32_16x16x32_bf16 v[92:95], v[132:135], v[164:167], v[92:95]
	v_mfma_f32_16x16x32_bf16 v[84:87], v[140:143], v[164:167], v[84:87]
	v_mfma_f32_16x16x32_bf16 v[76:79], v[132:135], v[172:175], v[76:79]
	v_mfma_f32_16x16x32_bf16 v[68:71], v[140:143], v[172:175], v[68:71]
	s_setprio 0
	s_barrier
	s_add_i32 s40, 0, 0x1c000
	s_add_i32 s41, s68, s33
	v_add_u32_e32 v204, s40, v183
	v_lshl_add_u64 v[208:209], v[208:209], 0, s[96:97]
	s_mov_b32 m0, s41
	ds_read_b128 v[176:179], v204
	ds_read_b128 v[196:199], v204 offset:1024
	ds_read_b128 v[200:203], v204 offset:2048
	ds_read_b128 v[204:207], v204 offset:3072
	global_load_lds_dwordx4 v[208:209], off
	s_add_i32 m0, s41, 0x2000
	v_lshl_add_u64 v[208:209], v[210:211], 0, s[96:97]
	global_load_lds_dwordx4 v[208:209], off
	s_barrier
	s_waitcnt lgkmcnt(0)
	s_setprio 1
	v_mfma_f32_16x16x32_bf16 v[120:123], v[176:179], v[144:147], v[120:123]
	v_mfma_f32_16x16x32_bf16 v[112:115], v[200:203], v[144:147], v[112:115]
	v_mfma_f32_16x16x32_bf16 v[104:107], v[176:179], v[152:155], v[104:107]
	v_mfma_f32_16x16x32_bf16 v[96:99], v[200:203], v[152:155], v[96:99]
	v_mfma_f32_16x16x32_bf16 v[88:91], v[176:179], v[160:163], v[88:91]
	v_mfma_f32_16x16x32_bf16 v[80:83], v[200:203], v[160:163], v[80:83]
	v_mfma_f32_16x16x32_bf16 v[72:75], v[176:179], v[168:171], v[72:75]
	v_mfma_f32_16x16x32_bf16 v[64:67], v[200:203], v[168:171], v[64:67]
	v_mfma_f32_16x16x32_bf16 v[120:123], v[196:199], v[148:151], v[120:123]
	v_mfma_f32_16x16x32_bf16 v[112:115], v[204:207], v[148:151], v[112:115]
	v_mfma_f32_16x16x32_bf16 v[104:107], v[196:199], v[156:159], v[104:107]
	v_mfma_f32_16x16x32_bf16 v[96:99], v[204:207], v[156:159], v[96:99]
	v_mfma_f32_16x16x32_bf16 v[88:91], v[196:199], v[164:167], v[88:91]
	v_mfma_f32_16x16x32_bf16 v[80:83], v[204:207], v[164:167], v[80:83]
	v_mfma_f32_16x16x32_bf16 v[72:75], v[196:199], v[172:175], v[72:75]
	v_mfma_f32_16x16x32_bf16 v[64:67], v[204:207], v[172:175], v[64:67]
	s_setprio 0
	s_mov_b32 m0, s8
	v_lshl_add_u64 v[208:209], v[212:213], 0, s[96:97]
	s_barrier
	ds_read_b128 v[144:147], v239 offset:49152
	ds_read_b128 v[148:151], v239 offset:50176
	ds_read_b128 v[152:155], v239 offset:51200
	ds_read_b128 v[156:159], v239 offset:52224
	ds_read_b128 v[160:163], v239 offset:53248
	ds_read_b128 v[164:167], v239 offset:54272
	ds_read_b128 v[168:171], v239 offset:55296
	ds_read_b128 v[172:175], v239 offset:56320
	global_load_lds_dwordx4 v[208:209], off
	s_mov_b32 m0, s9
	v_lshl_add_u64 v[208:209], v[214:215], 0, s[96:97]
	global_load_lds_dwordx4 v[208:209], off
	s_barrier
	s_waitcnt lgkmcnt(0)
	s_setprio 1
	v_mfma_f32_16x16x32_bf16 v[60:63], v[128:131], v[144:147], v[60:63]
	v_mfma_f32_16x16x32_bf16 v[52:55], v[136:139], v[144:147], v[52:55]
	v_mfma_f32_16x16x32_bf16 v[44:47], v[128:131], v[152:155], v[44:47]
	v_mfma_f32_16x16x32_bf16 v[36:39], v[136:139], v[152:155], v[36:39]
	v_mfma_f32_16x16x32_bf16 v[28:31], v[128:131], v[160:163], v[28:31]
	v_mfma_f32_16x16x32_bf16 v[20:23], v[136:139], v[160:163], v[20:23]
	v_mfma_f32_16x16x32_bf16 v[12:15], v[128:131], v[168:171], v[12:15]
	v_mfma_f32_16x16x32_bf16 v[4:7], v[136:139], v[168:171], v[4:7]
	v_mfma_f32_16x16x32_bf16 v[60:63], v[132:135], v[148:151], v[60:63]
	v_mfma_f32_16x16x32_bf16 v[52:55], v[140:143], v[148:151], v[52:55]
	v_mfma_f32_16x16x32_bf16 v[44:47], v[132:135], v[156:159], v[44:47]
	v_mfma_f32_16x16x32_bf16 v[36:39], v[140:143], v[156:159], v[36:39]
	v_mfma_f32_16x16x32_bf16 v[28:31], v[132:135], v[164:167], v[28:31]
	v_mfma_f32_16x16x32_bf16 v[20:23], v[140:143], v[164:167], v[20:23]
	v_mfma_f32_16x16x32_bf16 v[12:15], v[132:135], v[172:175], v[12:15]
	v_mfma_f32_16x16x32_bf16 v[4:7], v[140:143], v[172:175], v[4:7]
	s_setprio 0
	s_barrier
	s_add_i32 s40, s40, s33
	s_mov_b32 m0, s40
	v_lshl_add_u64 v[128:129], v[216:217], 0, s[96:97]
	global_load_lds_dwordx4 v[128:129], off
	s_add_i32 m0, s40, 0x2000
	v_lshl_add_u64 v[128:129], v[218:219], 0, s[96:97]
	global_load_lds_dwordx4 v[128:129], off
	s_waitcnt vmcnt(6)
	s_barrier
	s_setprio 1
	v_mfma_f32_16x16x32_bf16 v[56:59], v[176:179], v[144:147], v[56:59]
	v_mfma_f32_16x16x32_bf16 v[48:51], v[200:203], v[144:147], v[48:51]
	v_mfma_f32_16x16x32_bf16 v[40:43], v[176:179], v[152:155], v[40:43]
	v_mfma_f32_16x16x32_bf16 v[32:35], v[200:203], v[152:155], v[32:35]
	v_mfma_f32_16x16x32_bf16 v[24:27], v[176:179], v[160:163], v[24:27]
	v_mfma_f32_16x16x32_bf16 v[16:19], v[200:203], v[160:163], v[16:19]
	v_mfma_f32_16x16x32_bf16 v[8:11], v[176:179], v[168:171], v[8:11]
	v_mfma_f32_16x16x32_bf16 v[0:3], v[200:203], v[168:171], v[0:3]
	v_mfma_f32_16x16x32_bf16 v[56:59], v[196:199], v[148:151], v[56:59]
	v_mfma_f32_16x16x32_bf16 v[48:51], v[204:207], v[148:151], v[48:51]
	v_mfma_f32_16x16x32_bf16 v[40:43], v[196:199], v[156:159], v[40:43]
	v_mfma_f32_16x16x32_bf16 v[32:35], v[204:207], v[156:159], v[32:35]
	v_mfma_f32_16x16x32_bf16 v[24:27], v[196:199], v[164:167], v[24:27]
	v_mfma_f32_16x16x32_bf16 v[16:19], v[204:207], v[164:167], v[16:19]
	v_mfma_f32_16x16x32_bf16 v[8:11], v[196:199], v[172:175], v[8:11]
	v_mfma_f32_16x16x32_bf16 v[0:3], v[204:207], v[172:175], v[0:3]
	s_setprio 0
	s_add_u32 s0, s0, 0x100
	s_addc_u32 s1, s1, 0
	s_add_u32 s70, s70, 0x100
	s_addc_u32 s71, s71, 0
	s_cmp_ge_u32 s72, s7
	s_mov_b32 s40, s72
	s_barrier
	s_cbranch_scc0 .LBB0_141
	v_lshl_add_u32 v196, s19, 8, v181
	s_cmp_lt_i32 s78, 2
	s_mov_b64 s[0:1], -1
	s_cbranch_scc1 .LBB0_223
	s_cmp_gt_i32 s78, 2
	s_cbranch_scc0 .LBB0_220
	s_lshl_b32 s0, s18, 8
	s_ashr_i32 s68, s18, 1
	s_and_b32 s0, s0, 0x100
	s_cmp_lt_i32 s68, 2
	v_or_b32_e32 v148, s0, v238
	s_cselect_b64 s[0:1], -1, 0
	s_lshl_b32 s40, s68, 9
	s_add_i32 s80, s40, 0xfffffc00
	v_readlane_b32 s48, v241, 0
	s_lshl_b64 s[70:71], s[80:81], 2
	v_readlane_b32 s62, v241, 14
	v_readlane_b32 s63, v241, 15
	s_add_u32 s69, s62, s70
	s_addc_u32 s80, s63, s71
	s_ashr_i32 s41, s40, 31
	v_readlane_b32 s58, v241, 10
	s_lshl_b64 s[40:41], s[40:41], 2
	v_readlane_b32 s59, v241, 11
	s_add_u32 s99, s58, s40
	s_mov_b32 s83, s82
	s_addc_u32 s82, s59, s41
	s_cmp_lt_i32 s68, 4
	s_cselect_b64 s[72:73], -1, 0
	s_cmp_gt_i32 s68, 3
	s_cselect_b64 s[70:71], -1, 0
	v_mov_b32_e32 v132, 0
	s_and_b64 vcc, exec, s[70:71]
	v_lshlrev_b32_e32 v136, 2, v148
	v_mov_b32_e32 v140, 0
	v_mov_b32_e32 v141, v132
	v_mov_b32_e32 v142, 0
	v_mov_b32_e32 v143, 0
	v_readlane_b32 s49, v241, 1
	v_readlane_b32 s50, v241, 2
	v_readlane_b32 s51, v241, 3
	v_readlane_b32 s52, v241, 4
	v_readlane_b32 s53, v241, 5
	v_readlane_b32 s54, v241, 6
	v_readlane_b32 s55, v241, 7
	v_readlane_b32 s56, v241, 8
	v_readlane_b32 s57, v241, 9
	v_readlane_b32 s60, v241, 12
	v_readlane_b32 s61, v241, 13
	s_cbranch_vccnz .LBB0_146
	s_and_b64 s[40:41], s[0:1], exec
	s_cselect_b32 s41, s82, s80
	s_cselect_b32 s40, s99, s69
	global_load_dwordx4 v[140:143], v136, s[40:41]
